# gemm_y phases (DN1, OUT, DN2) also moved to the 256x256 8-phase core: 1 prompt tile per block + streamed sample split-K units
# speedup vs baseline: 1.8081x; 1.0137x over previous
; DI void gemm_y(const Params& p, const bf16_t* A, int lda, size_t woff, int K, int kper, int bid, int nb, char* smem, const int tid) {
;     const bf16_t* Bt = (const bf16_t*)(p.ws + woff);
;     TileIter ti; ti.init(64, 8, bid, nb);
;     int tm, tn, tm2 = 0, tn2 = 0;
;     bool have = ti.next(tm, tn);
;     Ring rg; rg.st = 0; rg.primed = 0;
;     for (; have; tm = tm2, tn = tn2) {
;         have = ti.next(tm2, tn2);
;         const int m0 = tm * 256, n0 = tn * 128;
;         f32x4 acc[4][4]; zero_acc(acc);
;         gemm_stream(A, lda, Bt, K, K, m0, n0, have, tm2 * 256, tn2 * 128, smem, acc, tid, rg);
;         epi_y<0>(p, acc, m0, n0, tid);
;     }
;     const int S = (K / 64) / kper;
;     for (int u = bid; u < 8 * S; u += nb) {
;         const int tile = u / S, part = u - tile * S, m0 = NP, n0 = tile * 128;
;         f32x4 acc[4][4]; zero_acc(acc);
;         gemm_mainloop(A + part * kper * 64, lda, Bt + part * kper * 64, K, kper * 64, m0, n0, smem, acc, tid);
;         epi_y<2>(p, acc, m0, n0, tid, part);
;     }
; DI void run_phase(const Params& pk, int ph, int bid_, int nb, char* smem) {
;     ...
;     switch (s) {
;     case 0: gemm_gu(p, W_GU1, bid, nb, smem, tid); break;
;     case 1: gemm_y(p, (const bf16_t*)(p.ws + B_ACT), DFF, W_DN1, DFF, 4, bid, nb, smem, tid); break;
;     case 2: rowpass(p, false, 0.5f, p.in[12] + l * DM, p.in[15] + l * DM, 11, bid, nb, tid); break;
;     case 3: gemm_in(p, l, bid, nb, smem, tid); break;
;     case 4: post_phase(p, l, bid, nb, tid); break;
;     case 5: gemm_uqkv(p, bid, nb, smem, tid); break;
;     case 6: attn_phase(p, bid, nb, smem, tid); break;
;     case 7: onorm_pass(p, p.in[23] + l * DM, bid, nb, tid); break;
;     case 8: gemm_y(p, (const bf16_t*)(p.ws + B_XN), DM, W_OUT, DM, 2, bid, nb, smem, tid); break;
;     case 9: rowpass(p, false, 1.0f, p.in[16] + l * DM, p.in[25] + l * DM, 8, bid, nb, tid); break;
;     case 10: gemm_gu(p, W_GU2, bid, nb, smem, tid); break;
;     case 11: gemm_y(p, (const bf16_t*)(p.ws + B_ACT), DFF, W_DN2, DFF, 4, bid, nb, smem, tid); break;
.LBB0_160:
	s_andn2_b64 vcc, exec, s[0:1]
	s_cbranch_vccnz .LBB0_194
	s_mov_b32 s61, 0x2220000
	s_branch .Lgyd_entry

; DI void gemm_y(const Params& p, const bf16_t* A, int lda, size_t woff, int K, int kper, int bid, int nb, char* smem, const int tid) {
;     const bf16_t* Bt = (const bf16_t*)(p.ws + woff);
;     TileIter ti; ti.init(64, 8, bid, nb);
;     int tm, tn, tm2 = 0, tn2 = 0;
;     bool have = ti.next(tm, tn);
;     Ring rg; rg.st = 0; rg.primed = 0;
;     for (; have; tm = tm2, tn = tn2) {
;         have = ti.next(tm2, tn2);
;         const int m0 = tm * 256, n0 = tn * 128;
;         f32x4 acc[4][4]; zero_acc(acc);
;         gemm_stream(A, lda, Bt, K, K, m0, n0, have, tm2 * 256, tn2 * 128, smem, acc, tid, rg);
;         epi_y<0>(p, acc, m0, n0, tid);
;     }
;     const int S = (K / 64) / kper;
;     for (int u = bid; u < 8 * S; u += nb) {
;         const int tile = u / S, part = u - tile * S, m0 = NP, n0 = tile * 128;
;         f32x4 acc[4][4]; zero_acc(acc);
;         gemm_mainloop(A + part * kper * 64, lda, Bt + part * kper * 64, K, kper * 64, m0, n0, smem, acc, tid);
;         epi_y<2>(p, acc, m0, n0, tid, part);
;     }
; DI void run_phase(const Params& pk, int ph, int bid_, int nb, char* smem) {
;     ...
;     case 8: gemm_y(p, (const bf16_t*)(p.ws + B_XN), DM, W_OUT, DM, 2, bid, nb, smem, tid); break;
.LBB0_237:
	s_andn2_b64 vcc, exec, s[0:1]
	s_cbranch_vccnz .LBB0_276
	v_readlane_b32 s0, v231, 5
	s_cmp_gt_i32 s0, 7
	s_mov_b64 s[0:1], -1
	s_cbranch_scc0 .LBB0_272
	s_mov_b32 s61, 0x1520000
	s_branch .Lgyo_entry

; DI void gemm_y(const Params& p, const bf16_t* A, int lda, size_t woff, int K, int kper, int bid, int nb, char* smem, const int tid) {
;     const bf16_t* Bt = (const bf16_t*)(p.ws + woff);
;     TileIter ti; ti.init(64, 8, bid, nb);
;     int tm, tn, tm2 = 0, tn2 = 0;
;     bool have = ti.next(tm, tn);
;     Ring rg; rg.st = 0; rg.primed = 0;
;     for (; have; tm = tm2, tn = tn2) {
;         have = ti.next(tm2, tn2);
;         const int m0 = tm * 256, n0 = tn * 128;
;         f32x4 acc[4][4]; zero_acc(acc);
;         gemm_stream(A, lda, Bt, K, K, m0, n0, have, tm2 * 256, tn2 * 128, smem, acc, tid, rg);
;         epi_y<0>(p, acc, m0, n0, tid);
;     }
;     const int S = (K / 64) / kper;
;     for (int u = bid; u < 8 * S; u += nb) {
;         const int tile = u / S, part = u - tile * S, m0 = NP, n0 = tile * 128;
;         f32x4 acc[4][4]; zero_acc(acc);
;         gemm_mainloop(A + part * kper * 64, lda, Bt + part * kper * 64, K, kper * 64, m0, n0, smem, acc, tid);
;         epi_y<2>(p, acc, m0, n0, tid, part);
;     }
; DI void run_phase(const Params& pk, int ph, int bid_, int nb, char* smem) {
;     ...
;     case 1: gemm_y(p, (const bf16_t*)(p.ws + B_ACT), DFF, W_DN1, DFF, 4, bid, nb, smem, tid); break;
.LBB0_715:
	s_mov_b64 s[62:63], s[46:47]
	s_andn2_b64 vcc, exec, s[0:1]
	s_cbranch_vccnz .LBB0_748
	s_mov_b32 s61, 0xb00000
	s_branch .Lgyd_entry

;     DI void init(int ntm_, int ntn_, int bid, int nb) {
;         ntm = ntm_; ntn = ntn_;
;         const int nt = ntm * ntn;
;         if ((nb & 7) == 0) { const int x = bid & 7, per = (nt + 7) >> 3; L = x * per + (bid >> 3); end = min((x + 1) * per, nt); step = nb >> 3; }
;         else { L = bid; end = nt; step = nb; }
;     }
; DI void gemm_y(const Params& p, const bf16_t* A, int lda, size_t woff, int K, int kper, int bid, int nb, char* smem, const int tid) {
;     const bf16_t* Bt = (const bf16_t*)(p.ws + woff);
;     TileIter ti; ti.init(64, 8, bid, nb);
;     int tm, tn, tm2 = 0, tn2 = 0;
;     bool have = ti.next(tm, tn);
;     Ring rg; rg.st = 0; rg.primed = 0;
;     for (; have; tm = tm2, tn = tn2) {
;         have = ti.next(tm2, tn2);
;         const int m0 = tm * 256, n0 = tn * 128;
;         f32x4 acc[4][4]; zero_acc(acc);
;         gemm_stream(A, lda, Bt, K, K, m0, n0, have, tm2 * 256, tn2 * 128, smem, acc, tid, rg);
;         epi_y<0>(p, acc, m0, n0, tid);
;     }
;     const int S = (K / 64) / kper;
;     for (int u = bid; u < 8 * S; u += nb) {
;         const int tile = u / S, part = u - tile * S, m0 = NP, n0 = tile * 128;
;         f32x4 acc[4][4]; zero_acc(acc);
;         gemm_mainloop(A + part * kper * 64, lda, Bt + part * kper * 64, K, kper * 64, m0, n0, smem, acc, tid);
;         epi_y<2>(p, acc, m0, n0, tid, part);
;     }
.Lgyd_entry:
	v_readlane_b32 s96, v240, 0
	v_readlane_b32 s97, v238, 54
	v_readfirstlane_b32 s10, v193
	s_nop 3
	s_lshr_b32 s10, s10, 6
	s_lshr_b32 s33, s10, 2
	s_and_b32 s36, s10, 3
	s_lshl_b32 s39, s10, 11
	s_add_i32 s39, s39, 16
	s_and_b32 s1, s97, 7
	s_cmp_eq_u32 s1, 0
	s_cbranch_scc0 .Lgyd_simple
	s_and_b32 s1, s96, 7
	s_lshr_b32 s2, s96, 3
	s_lshl_b32 s3, s1, 5
	s_add_i32 s51, s3, s2
	s_add_i32 s52, s3, 32
	s_lshr_b32 s53, s97, 3
	s_branch .Lgyd_ranged
.Lgyd_simple:
	s_mov_b32 s51, s96
	s_movk_i32 s52, 0x100
	s_mov_b32 s53, s97
.Lgyd_ranged:
	s_cmp_lt_u32 s51, s52
	s_cbranch_scc1 .Lgyd_first_main
	s_cmp_lt_u32 s96, 44
	s_cbranch_scc0 .LBB0_860
	s_mov_b32 s55, 1
	s_mov_b32 s51, s96
	s_mul_i32 s1, s51, 0x1746
	s_lshr_b32 s58, s1, 16
	s_mul_i32 s1, s58, 11
	s_sub_u32 s57, s51, s1
	s_mul_i32 s2, s10, 0x16000
	s_lshl_b32 s3, s57, 9
	s_add_u32 s1, s2, 0x5800000
	s_add_u32 s1, s1, s3
	s_add_u32 s66, s88, s1
	s_addc_u32 s67, s89, 0
	s_add_u32 s66, s66, 0x52c0000
	s_addc_u32 s67, s67, 0
	s_add_u32 s68, s66, 0xb0000
	s_addc_u32 s69, s67, 0
	s_mul_i32 s1, s58, 0x160000
	s_add_u32 s1, s1, s2
	s_add_u32 s1, s1, s3
	s_add_u32 s1, s1, s61
	s_add_u32 s70, s88, s1
	s_addc_u32 s71, s89, 0
	s_add_u32 s72, s70, 0xb0000
	s_addc_u32 s73, s71, 0
	s_branch .Lgyd_lanes
.Lgyd_first_main:
	s_mov_b32 s55, 0
	s_lshr_b32 s1, s51, 5
	s_and_b32 s2, s51, 31
	s_lshr_b32 s58, s2, 3
	s_and_b32 s2, s2, 7
	s_lshl_b32 s1, s1, 3
	s_add_i32 s57, s1, s2
	s_mul_i32 s2, s10, 0x16000
	s_mul_i32 s1, s57, 0x160000
	s_add_u32 s1, s1, s2
	s_add_u32 s66, s88, s1
	s_addc_u32 s67, s89, 0
	s_add_u32 s66, s66, 0x52c0000
	s_addc_u32 s67, s67, 0
	s_add_u32 s68, s66, 0xb0000
	s_addc_u32 s69, s67, 0
	s_mul_i32 s1, s58, 0x160000
	s_add_u32 s1, s1, s2
	s_add_u32 s1, s1, s61
	s_add_u32 s70, s88, s1
	s_addc_u32 s71, s89, 0
	s_add_u32 s72, s70, 0xb0000
	s_addc_u32 s73, s71, 0
.Lgyd_lanes:
	v_and_b32_e32 v190, 63, v193
	v_and_b32_e32 v191, 15, v190
	v_lshrrev_b32_e32 v17, 4, v190
	v_lshrrev_b32_e32 v18, 3, v190
	v_and_b32_e32 v19, 7, v190
	v_xor_b32_e32 v195, v19, v17
	v_lshlrev_b32_e32 v195, 4, v195
	s_mov_b32 s1, 0x1600
	v_mad_u32_u24 v184, v18, s1, v195
	v_or_b32_e32 v195, 4, v17
	v_xor_b32_e32 v195, v19, v195
	v_lshlrev_b32_e32 v195, 4, v195
	v_add_u32_e32 v227, 8, v18
	v_mad_u32_u24 v185, v227, s1, v195
	v_lshrrev_b32_e32 v195, 1, v191
	v_xor_b32_e32 v195, v17, v195
	v_lshlrev_b32_e32 v195, 4, v195
	s_lshl_b32 s1, s33, 6
	v_add_u32_e32 v227, s1, v191
	v_lshl_add_u32 v186, v227, 7, v195
	v_xor_b32_e32 v187, 64, v186
	v_lshlrev_b32_e32 v228, 11, v227
	s_lshl_b32 s1, s36, 5
	v_add_u32_e32 v227, s1, v191
	v_lshl_add_u32 v188, v227, 7, v195
	v_add_u32_e32 v188, 0x10000, v188
	v_xor_b32_e32 v189, 64, v188
	s_lshl_b32 s1, s36, 6
	v_lshl_add_u32 v229, v17, 3, s1
	v_add_u32_e32 v237, v228, v229
	s_add_i32 m0, s39, 0x10000
	s_nop 0
	global_load_lds_dwordx4 v184, s[70:71]
	s_add_i32 m0, s39, 0x10400
	s_nop 0
	global_load_lds_dwordx4 v185, s[70:71]
	s_add_u32 s70, s70, 0x80
	s_addc_u32 s71, s71, 0
	s_add_i32 m0, s39, 0x0
	s_nop 0
	global_load_lds_dwordx4 v184, s[66:67]
	s_add_i32 m0, s39, 0x400
	s_nop 0
	global_load_lds_dwordx4 v185, s[66:67]
	s_add_u32 s66, s66, 0x80
	s_addc_u32 s67, s67, 0
	s_add_i32 m0, s39, 0x14000
	s_nop 0
	global_load_lds_dwordx4 v184, s[72:73]
	s_add_i32 m0, s39, 0x14400
	s_nop 0
	global_load_lds_dwordx4 v185, s[72:73]
	s_add_u32 s72, s72, 0x80
	s_addc_u32 s73, s73, 0
	s_add_i32 m0, s39, 0x4000
	s_nop 0
	global_load_lds_dwordx4 v184, s[68:69]
	s_add_i32 m0, s39, 0x4400
	s_nop 0
	global_load_lds_dwordx4 v185, s[68:69]
	s_add_u32 s68, s68, 0x80
	s_addc_u32 s69, s69, 0
	s_cmp_eq_u32 s33, 0
	s_cbranch_scc1 .Lgyd_lead
	s_barrier

; DI void zero_acc(f32x4 (&acc)[4][4]) {
; #pragma unroll
;     for (int i = 0; i < 4; ++i)
; #pragma unroll
;         for (int j = 0; j < 4; ++j) acc[i][j] = (f32x4){0.f, 0.f, 0.f, 0.f};
; }
; DI void gemm_y(const Params& p, const bf16_t* A, int lda, size_t woff, int K, int kper, int bid, int nb, char* smem, const int tid) {
;     ...
;     for (; have; tm = tm2, tn = tn2) {
;         have = ti.next(tm2, tn2);
;         const int m0 = tm * 256, n0 = tn * 128;
;         f32x4 acc[4][4]; zero_acc(acc);
;         gemm_stream(A, lda, Bt, K, K, m0, n0, have, tm2 * 256, tn2 * 128, smem, acc, tid, rg);
;         epi_y<0>(p, acc, m0, n0, tid);
;     }
;     const int S = (K / 64) / kper;
;     for (int u = bid; u < 8 * S; u += nb) {
;         const int tile = u / S, part = u - tile * S, m0 = NP, n0 = tile * 128;
;         f32x4 acc[4][4]; zero_acc(acc);
;         gemm_mainloop(A + part * kper * 64, lda, Bt + part * kper * 64, K, kper * 64, m0, n0, smem, acc, tid);
;         epi_y<2>(p, acc, m0, n0, tid, part);
;     }
.Lgyd_item:
	s_cmp_eq_u32 s55, 0
	s_cbranch_scc0 .Lgyd_nx_unit
	s_add_u32 s76, s51, s53
	s_cmp_lt_u32 s76, s52
	s_cbranch_scc0 .Lgyd_nx_first_unit
	s_mov_b32 s54, 1
	s_mov_b32 s93, 0
	s_lshr_b32 s1, s76, 5
	s_and_b32 s2, s76, 31
	s_lshr_b32 s60, s2, 3
	s_and_b32 s2, s2, 7
	s_lshl_b32 s1, s1, 3
	s_add_i32 s59, s1, s2
	s_mul_i32 s2, s10, 0x16000
	s_mul_i32 s1, s59, 0x160000
	s_add_u32 s1, s1, s2
	s_add_u32 s74, s88, s1
	s_addc_u32 s75, s89, 0
	s_add_u32 s74, s74, 0x52c0000
	s_addc_u32 s75, s75, 0
	s_add_u32 s78, s74, 0xb0000
	s_addc_u32 s79, s75, 0
	s_mul_i32 s1, s60, 0x160000
	s_add_u32 s1, s1, s2
	s_add_u32 s1, s1, s61
	s_add_u32 s80, s88, s1
	s_addc_u32 s81, s89, 0
	s_add_u32 s82, s80, 0xb0000
	s_addc_u32 s83, s81, 0
	s_branch .Lgyd_nx_done
.Lgyd_nx_first_unit:
	s_mov_b32 s76, s96
	s_branch .Lgyd_nx_unit_chk
.Lgyd_nx_unit:
	s_add_u32 s76, s51, s97
.Lgyd_nx_unit_chk:
	s_mov_b32 s54, 0
	s_cmp_lt_u32 s76, 44
	s_cbranch_scc0 .Lgyd_nx_done
	s_mov_b32 s54, 1
	s_mov_b32 s93, 1
	s_mul_i32 s1, s76, 0x1746
	s_lshr_b32 s60, s1, 16
	s_mul_i32 s1, s60, 11
	s_sub_u32 s59, s76, s1
	s_mul_i32 s2, s10, 0x16000
	s_lshl_b32 s3, s59, 9
	s_add_u32 s1, s2, 0x5800000
	s_add_u32 s1, s1, s3
	s_add_u32 s74, s88, s1
	s_addc_u32 s75, s89, 0
	s_add_u32 s74, s74, 0x52c0000
	s_addc_u32 s75, s75, 0
	s_add_u32 s78, s74, 0xb0000
	s_addc_u32 s79, s75, 0
	s_mul_i32 s1, s60, 0x160000
	s_add_u32 s1, s1, s2
	s_add_u32 s1, s1, s3
	s_add_u32 s1, s1, s61
	s_add_u32 s80, s88, s1
	s_addc_u32 s81, s89, 0
	s_add_u32 s82, s80, 0xb0000
	s_addc_u32 s83, s81, 0
.Lgyd_nx_done:
	v_mov_b64_e32 v[24:25], 0
	v_mov_b64_e32 v[26:27], 0
	v_mov_b64_e32 v[28:29], 0
	v_mov_b64_e32 v[30:31], 0
	v_mov_b64_e32 v[32:33], 0
	v_mov_b64_e32 v[34:35], 0
	v_mov_b64_e32 v[36:37], 0
	v_mov_b64_e32 v[38:39], 0
	v_mov_b64_e32 v[40:41], 0
	v_mov_b64_e32 v[42:43], 0
	v_mov_b64_e32 v[44:45], 0
	v_mov_b64_e32 v[46:47], 0
	v_mov_b64_e32 v[48:49], 0
	v_mov_b64_e32 v[50:51], 0
	v_mov_b64_e32 v[52:53], 0
	v_mov_b64_e32 v[54:55], 0
	v_mov_b64_e32 v[56:57], 0
	v_mov_b64_e32 v[58:59], 0
	v_mov_b64_e32 v[60:61], 0
	v_mov_b64_e32 v[62:63], 0
	v_mov_b64_e32 v[64:65], 0
	v_mov_b64_e32 v[66:67], 0
	v_mov_b64_e32 v[68:69], 0
	v_mov_b64_e32 v[70:71], 0
	v_mov_b64_e32 v[72:73], 0
	v_mov_b64_e32 v[74:75], 0
	v_mov_b64_e32 v[76:77], 0
	v_mov_b64_e32 v[78:79], 0
	v_mov_b64_e32 v[80:81], 0
	v_mov_b64_e32 v[82:83], 0
	v_mov_b64_e32 v[84:85], 0
	v_mov_b64_e32 v[86:87], 0
	v_mov_b64_e32 v[88:89], 0
	v_mov_b64_e32 v[90:91], 0
	v_mov_b64_e32 v[92:93], 0
	v_mov_b64_e32 v[94:95], 0
	v_mov_b64_e32 v[96:97], 0
	v_mov_b64_e32 v[98:99], 0
	v_mov_b64_e32 v[100:101], 0
	v_mov_b64_e32 v[102:103], 0
	v_mov_b64_e32 v[104:105], 0
	v_mov_b64_e32 v[106:107], 0
	v_mov_b64_e32 v[108:109], 0
	v_mov_b64_e32 v[110:111], 0
	v_mov_b64_e32 v[112:113], 0
	v_mov_b64_e32 v[114:115], 0
	v_mov_b64_e32 v[116:117], 0
	v_mov_b64_e32 v[118:119], 0
	v_mov_b64_e32 v[120:121], 0
	v_mov_b64_e32 v[122:123], 0
	v_mov_b64_e32 v[124:125], 0
	v_mov_b64_e32 v[126:127], 0
	v_mov_b64_e32 v[128:129], 0
	v_mov_b64_e32 v[130:131], 0
	v_mov_b64_e32 v[132:133], 0
	v_mov_b64_e32 v[134:135], 0
	v_mov_b64_e32 v[136:137], 0
	v_mov_b64_e32 v[138:139], 0
	v_mov_b64_e32 v[140:141], 0
	v_mov_b64_e32 v[142:143], 0
	v_mov_b64_e32 v[144:145], 0
	v_mov_b64_e32 v[146:147], 0
	v_mov_b64_e32 v[148:149], 0
	v_mov_b64_e32 v[150:151], 0
	s_cmp_eq_u32 s55, 0
	s_cselect_b32 s0, 21, 1
	s_add_u32 s0, s0, s54
	s_cmp_eq_u32 s0, 0
	s_cbranch_scc1 .Lgyd_kdone

; #define LAS __attribute__((address_space(3)))
; #define BAR() { __builtin_amdgcn_sched_barrier(0); __builtin_amdgcn_s_barrier(); asm volatile("" ::: "memory"); __builtin_amdgcn_sched_barrier(0); }
; DI void gemm_stream2(const bf16_t* __restrict__ A, int lda, const bf16_t* __restrict__ Bt, int ldb, int K, int m0, int n0, ...
;     ...
;     for (int kt = 0; kt < nk; ++kt) {
;         const bool pf = (kt + 2 < nk) || has_next, more = (kt + 1 < nk) || has_next;
;         const bf16_t* pa = (kt + 2 < nk) ? ga + (kt + 2) * 64 : gan + (kt + 2 - nk) * 64;
;         const bf16_t* pb = (kt + 2 < nk) ? gb + (kt + 2) * 64 : gbn + (kt + 2 - nk) * 64;
;         const int plda = (kt + 2 < nk) ? lda : ldan, pldb = (kt + 2 < nk) ? ldb : ldbn;
;         const int s2 = st >= 1 ? st - 1 : 2;
;         const LAS char* base = lds + st * 49152;
; #pragma unroll
;         for (int ks = 0; ks < 2; ++ks) {
;             const unsigned fo = ks ? fo1 : fo0;
;             bf16x8 af[4], bfr[4];
; #pragma unroll
;             for (int i = 0; i < 4; ++i) { af[i] = *(const LAS bf16x8*)(base + aoff + i * 2048 + fo); bfr[i] = *(const LAS bf16x8*)(base + boff + i * 2048 + fo); }
;             if (ks == 1 && more) { if (pf) asm volatile("s_waitcnt vmcnt(3)" ::: "memory"); else asm volatile("s_waitcnt vmcnt(0)" ::: "memory"); }
;             if (pf) { PIECE(s2, ks * 3 + 0); PIECE(s2, ks * 3 + 1); PIECE(s2, ks * 3 + 2); }
;             asm volatile("s_waitcnt lgkmcnt(0)" ::: "memory");
;             BAR();
;             __builtin_amdgcn_s_setprio(1);
; #pragma unroll
;             for (int mi = 0; mi < 4; ++mi)
; #pragma unroll
;                 for (int ni = 0; ni < 4; ++ni) acc[mi][ni] = __builtin_amdgcn_mfma_f32_16x16x32_bf16(bfr[ni], af[mi], acc[mi][ni], 0, 0, 0);
;             __builtin_amdgcn_s_setprio(0);
;             BAR();
;         }
;         st = st == 2 ? 0 : st + 1;
;     }
;     if (grp == 0) BAR();
.Lgyd_kdone:
	s_cmp_lg_u32 s54, 0
	s_cbranch_scc1 .Lgyd_epi
	ds_read_b128 v[0:3], v188 offset:16
	ds_read_b128 v[4:7], v189 offset:16
	ds_read_b128 v[8:11], v188 offset:2064
	ds_read_b128 v[12:15], v189 offset:2064
	ds_read_b128 v[152:155], v186 offset:16
	ds_read_b128 v[156:159], v187 offset:16
	ds_read_b128 v[160:163], v186 offset:2064
	ds_read_b128 v[164:167], v187 offset:2064
	ds_read_b128 v[168:171], v186 offset:4112
	ds_read_b128 v[172:175], v187 offset:4112
	ds_read_b128 v[176:179], v186 offset:6160
	ds_read_b128 v[180:183], v187 offset:6160
	s_add_i32 m0, s39, 0xc000
	s_nop 0
	global_load_lds_dwordx4 v184, s[68:69]
	s_add_i32 m0, s39, 0xc400
	s_nop 0
	global_load_lds_dwordx4 v185, s[68:69]
	s_add_u32 s68, s68, 0x80
	s_addc_u32 s69, s69, 0
	s_barrier
	s_waitcnt lgkmcnt(0)
	s_setprio 1
	v_mfma_f32_16x16x32_bf16 v[24:27], v[0:3], v[152:155], v[24:27]
	v_mfma_f32_16x16x32_bf16 v[28:31], v[8:11], v[152:155], v[28:31]
	v_mfma_f32_16x16x32_bf16 v[32:35], v[0:3], v[160:163], v[32:35]
	v_mfma_f32_16x16x32_bf16 v[36:39], v[8:11], v[160:163], v[36:39]
	v_mfma_f32_16x16x32_bf16 v[40:43], v[0:3], v[168:171], v[40:43]
	v_mfma_f32_16x16x32_bf16 v[44:47], v[8:11], v[168:171], v[44:47]
	v_mfma_f32_16x16x32_bf16 v[48:51], v[0:3], v[176:179], v[48:51]
	v_mfma_f32_16x16x32_bf16 v[52:55], v[8:11], v[176:179], v[52:55]
	v_mfma_f32_16x16x32_bf16 v[24:27], v[4:7], v[156:159], v[24:27]
	v_mfma_f32_16x16x32_bf16 v[28:31], v[12:15], v[156:159], v[28:31]
	v_mfma_f32_16x16x32_bf16 v[32:35], v[4:7], v[164:167], v[32:35]
	v_mfma_f32_16x16x32_bf16 v[36:39], v[12:15], v[164:167], v[36:39]
	v_mfma_f32_16x16x32_bf16 v[40:43], v[4:7], v[172:175], v[40:43]
	v_mfma_f32_16x16x32_bf16 v[44:47], v[12:15], v[172:175], v[44:47]
	v_mfma_f32_16x16x32_bf16 v[48:51], v[4:7], v[180:183], v[48:51]
	v_mfma_f32_16x16x32_bf16 v[52:55], v[12:15], v[180:183], v[52:55]
	s_setprio 0
	s_barrier
	ds_read_b128 v[196:199], v188 offset:16400
	ds_read_b128 v[200:203], v189 offset:16400
	ds_read_b128 v[204:207], v188 offset:18448
	ds_read_b128 v[208:211], v189 offset:18448
	s_barrier
	s_waitcnt lgkmcnt(0)
	s_setprio 1
	v_mfma_f32_16x16x32_bf16 v[56:59], v[196:199], v[152:155], v[56:59]
	v_mfma_f32_16x16x32_bf16 v[60:63], v[204:207], v[152:155], v[60:63]
	v_mfma_f32_16x16x32_bf16 v[64:67], v[196:199], v[160:163], v[64:67]
	v_mfma_f32_16x16x32_bf16 v[68:71], v[204:207], v[160:163], v[68:71]
	v_mfma_f32_16x16x32_bf16 v[72:75], v[196:199], v[168:171], v[72:75]
	v_mfma_f32_16x16x32_bf16 v[76:79], v[204:207], v[168:171], v[76:79]
	v_mfma_f32_16x16x32_bf16 v[80:83], v[196:199], v[176:179], v[80:83]
	v_mfma_f32_16x16x32_bf16 v[84:87], v[204:207], v[176:179], v[84:87]
	v_mfma_f32_16x16x32_bf16 v[56:59], v[200:203], v[156:159], v[56:59]
	v_mfma_f32_16x16x32_bf16 v[60:63], v[208:211], v[156:159], v[60:63]
	v_mfma_f32_16x16x32_bf16 v[64:67], v[200:203], v[164:167], v[64:67]
	v_mfma_f32_16x16x32_bf16 v[68:71], v[208:211], v[164:167], v[68:71]
	v_mfma_f32_16x16x32_bf16 v[72:75], v[200:203], v[172:175], v[72:75]
	v_mfma_f32_16x16x32_bf16 v[76:79], v[208:211], v[172:175], v[76:79]
	v_mfma_f32_16x16x32_bf16 v[80:83], v[200:203], v[180:183], v[80:83]
	v_mfma_f32_16x16x32_bf16 v[84:87], v[208:211], v[180:183], v[84:87]
	s_setprio 0
	s_barrier
	ds_read_b128 v[152:155], v186 offset:16400
	ds_read_b128 v[156:159], v187 offset:16400
	ds_read_b128 v[160:163], v186 offset:18448
	ds_read_b128 v[164:167], v187 offset:18448
	ds_read_b128 v[168:171], v186 offset:20496
	ds_read_b128 v[172:175], v187 offset:20496
	ds_read_b128 v[176:179], v186 offset:22544
	ds_read_b128 v[180:183], v187 offset:22544
	s_waitcnt vmcnt(4)
	s_barrier
	s_waitcnt lgkmcnt(0)
	s_setprio 1
	v_mfma_f32_16x16x32_bf16 v[88:91], v[0:3], v[152:155], v[88:91]
	v_mfma_f32_16x16x32_bf16 v[92:95], v[8:11], v[152:155], v[92:95]
	v_mfma_f32_16x16x32_bf16 v[96:99], v[0:3], v[160:163], v[96:99]
	v_mfma_f32_16x16x32_bf16 v[100:103], v[8:11], v[160:163], v[100:103]
	v_mfma_f32_16x16x32_bf16 v[104:107], v[0:3], v[168:171], v[104:107]
	v_mfma_f32_16x16x32_bf16 v[108:111], v[8:11], v[168:171], v[108:111]
	v_mfma_f32_16x16x32_bf16 v[112:115], v[0:3], v[176:179], v[112:115]
	v_mfma_f32_16x16x32_bf16 v[116:119], v[8:11], v[176:179], v[116:119]
	v_mfma_f32_16x16x32_bf16 v[88:91], v[4:7], v[156:159], v[88:91]
	v_mfma_f32_16x16x32_bf16 v[92:95], v[12:15], v[156:159], v[92:95]
	v_mfma_f32_16x16x32_bf16 v[96:99], v[4:7], v[164:167], v[96:99]
	v_mfma_f32_16x16x32_bf16 v[100:103], v[12:15], v[164:167], v[100:103]
	v_mfma_f32_16x16x32_bf16 v[104:107], v[4:7], v[172:175], v[104:107]
	v_mfma_f32_16x16x32_bf16 v[108:111], v[12:15], v[172:175], v[108:111]
	v_mfma_f32_16x16x32_bf16 v[112:115], v[4:7], v[180:183], v[112:115]
	v_mfma_f32_16x16x32_bf16 v[116:119], v[12:15], v[180:183], v[116:119]
	s_setprio 0
	s_setprio 1
	v_mfma_f32_16x16x32_bf16 v[120:123], v[196:199], v[152:155], v[120:123]
	v_mfma_f32_16x16x32_bf16 v[124:127], v[204:207], v[152:155], v[124:127]
	v_mfma_f32_16x16x32_bf16 v[128:131], v[196:199], v[160:163], v[128:131]
	v_mfma_f32_16x16x32_bf16 v[132:135], v[204:207], v[160:163], v[132:135]
	v_mfma_f32_16x16x32_bf16 v[136:139], v[196:199], v[168:171], v[136:139]
	v_mfma_f32_16x16x32_bf16 v[140:143], v[204:207], v[168:171], v[140:143]
	v_mfma_f32_16x16x32_bf16 v[144:147], v[196:199], v[176:179], v[144:147]
	v_mfma_f32_16x16x32_bf16 v[148:151], v[204:207], v[176:179], v[148:151]
	v_mfma_f32_16x16x32_bf16 v[120:123], v[200:203], v[156:159], v[120:123]
	v_mfma_f32_16x16x32_bf16 v[124:127], v[208:211], v[156:159], v[124:127]
	v_mfma_f32_16x16x32_bf16 v[128:131], v[200:203], v[164:167], v[128:131]
	v_mfma_f32_16x16x32_bf16 v[132:135], v[208:211], v[164:167], v[132:135]
	v_mfma_f32_16x16x32_bf16 v[136:139], v[200:203], v[172:175], v[136:139]
	v_mfma_f32_16x16x32_bf16 v[140:143], v[208:211], v[172:175], v[140:143]
	v_mfma_f32_16x16x32_bf16 v[144:147], v[200:203], v[180:183], v[144:147]
	v_mfma_f32_16x16x32_bf16 v[148:151], v[208:211], v[180:183], v[148:151]
	s_setprio 0
	s_barrier
; #define LAS __attribute__((address_space(3)))
; #define BAR() { __builtin_amdgcn_sched_barrier(0); __builtin_amdgcn_s_barrier(); asm volatile("" ::: "memory"); __builtin_amdgcn_sched_barrier(0); }
; DI void gemm_stream2(const bf16_t* __restrict__ A, int lda, const bf16_t* __restrict__ Bt, int ldb, int K, int m0, int n0, ...
;     ...
;     for (int kt = 0; kt < nk; ++kt) {
;         const bool pf = (kt + 2 < nk) || has_next, more = (kt + 1 < nk) || has_next;
;         const bf16_t* pa = (kt + 2 < nk) ? ga + (kt + 2) * 64 : gan + (kt + 2 - nk) * 64;
;         const bf16_t* pb = (kt + 2 < nk) ? gb + (kt + 2) * 64 : gbn + (kt + 2 - nk) * 64;
;         const int plda = (kt + 2 < nk) ? lda : ldan, pldb = (kt + 2 < nk) ? ldb : ldbn;
;         const int s2 = st >= 1 ? st - 1 : 2;
;         const LAS char* base = lds + st * 49152;
; #pragma unroll
;         for (int ks = 0; ks < 2; ++ks) {
;             const unsigned fo = ks ? fo1 : fo0;
;             bf16x8 af[4], bfr[4];
; #pragma unroll
;             for (int i = 0; i < 4; ++i) { af[i] = *(const LAS bf16x8*)(base + aoff + i * 2048 + fo); bfr[i] = *(const LAS bf16x8*)(base + boff + i * 2048 + fo); }
;             if (ks == 1 && more) { if (pf) asm volatile("s_waitcnt vmcnt(3)" ::: "memory"); else asm volatile("s_waitcnt vmcnt(0)" ::: "memory"); }
;             if (pf) { PIECE(s2, ks * 3 + 0); PIECE(s2, ks * 3 + 1); PIECE(s2, ks * 3 + 2); }
;             asm volatile("s_waitcnt lgkmcnt(0)" ::: "memory");
;             BAR();
;             __builtin_amdgcn_s_setprio(1);
; #pragma unroll
;             for (int mi = 0; mi < 4; ++mi)
; #pragma unroll
;                 for (int ni = 0; ni < 4; ++ni) acc[mi][ni] = __builtin_amdgcn_mfma_f32_16x16x32_bf16(bfr[ni], af[mi], acc[mi][ni], 0, 0, 0);
;             __builtin_amdgcn_s_setprio(0);
;             BAR();
;         }
;         st = st == 2 ? 0 : st + 1;
;     }
;     if (grp == 0) BAR();
;     rg.st = st; rg.primed = has_next ? 1 : 0;
	ds_read_b128 v[0:3], v188 offset:32784
	ds_read_b128 v[4:7], v189 offset:32784
	ds_read_b128 v[8:11], v188 offset:34832
	ds_read_b128 v[12:15], v189 offset:34832
	ds_read_b128 v[152:155], v186 offset:32784
	ds_read_b128 v[156:159], v187 offset:32784
	ds_read_b128 v[160:163], v186 offset:34832
	ds_read_b128 v[164:167], v187 offset:34832
	ds_read_b128 v[168:171], v186 offset:36880
	ds_read_b128 v[172:175], v187 offset:36880
	ds_read_b128 v[176:179], v186 offset:38928
	ds_read_b128 v[180:183], v187 offset:38928
	s_waitcnt vmcnt(2)
	s_barrier
	s_waitcnt lgkmcnt(0)
	s_setprio 1
	v_mfma_f32_16x16x32_bf16 v[24:27], v[0:3], v[152:155], v[24:27]
	v_mfma_f32_16x16x32_bf16 v[28:31], v[8:11], v[152:155], v[28:31]
	v_mfma_f32_16x16x32_bf16 v[32:35], v[0:3], v[160:163], v[32:35]
	v_mfma_f32_16x16x32_bf16 v[36:39], v[8:11], v[160:163], v[36:39]
	v_mfma_f32_16x16x32_bf16 v[40:43], v[0:3], v[168:171], v[40:43]
	v_mfma_f32_16x16x32_bf16 v[44:47], v[8:11], v[168:171], v[44:47]
	v_mfma_f32_16x16x32_bf16 v[48:51], v[0:3], v[176:179], v[48:51]
	v_mfma_f32_16x16x32_bf16 v[52:55], v[8:11], v[176:179], v[52:55]
	v_mfma_f32_16x16x32_bf16 v[24:27], v[4:7], v[156:159], v[24:27]
	v_mfma_f32_16x16x32_bf16 v[28:31], v[12:15], v[156:159], v[28:31]
	v_mfma_f32_16x16x32_bf16 v[32:35], v[4:7], v[164:167], v[32:35]
	v_mfma_f32_16x16x32_bf16 v[36:39], v[12:15], v[164:167], v[36:39]
	v_mfma_f32_16x16x32_bf16 v[40:43], v[4:7], v[172:175], v[40:43]
	v_mfma_f32_16x16x32_bf16 v[44:47], v[12:15], v[172:175], v[44:47]
	v_mfma_f32_16x16x32_bf16 v[48:51], v[4:7], v[180:183], v[48:51]
	v_mfma_f32_16x16x32_bf16 v[52:55], v[12:15], v[180:183], v[52:55]
	s_setprio 0
	s_barrier
	ds_read_b128 v[196:199], v188 offset:49168
	ds_read_b128 v[200:203], v189 offset:49168
	ds_read_b128 v[204:207], v188 offset:51216
	ds_read_b128 v[208:211], v189 offset:51216
	s_waitcnt vmcnt(0)
	s_barrier
	s_waitcnt lgkmcnt(0)
	s_setprio 1
	v_mfma_f32_16x16x32_bf16 v[56:59], v[196:199], v[152:155], v[56:59]
	v_mfma_f32_16x16x32_bf16 v[60:63], v[204:207], v[152:155], v[60:63]
	v_mfma_f32_16x16x32_bf16 v[64:67], v[196:199], v[160:163], v[64:67]
	v_mfma_f32_16x16x32_bf16 v[68:71], v[204:207], v[160:163], v[68:71]
	v_mfma_f32_16x16x32_bf16 v[72:75], v[196:199], v[168:171], v[72:75]
	v_mfma_f32_16x16x32_bf16 v[76:79], v[204:207], v[168:171], v[76:79]
	v_mfma_f32_16x16x32_bf16 v[80:83], v[196:199], v[176:179], v[80:83]
	v_mfma_f32_16x16x32_bf16 v[84:87], v[204:207], v[176:179], v[84:87]
	v_mfma_f32_16x16x32_bf16 v[56:59], v[200:203], v[156:159], v[56:59]
	v_mfma_f32_16x16x32_bf16 v[60:63], v[208:211], v[156:159], v[60:63]
	v_mfma_f32_16x16x32_bf16 v[64:67], v[200:203], v[164:167], v[64:67]
	v_mfma_f32_16x16x32_bf16 v[68:71], v[208:211], v[164:167], v[68:71]
	v_mfma_f32_16x16x32_bf16 v[72:75], v[200:203], v[172:175], v[72:75]
	v_mfma_f32_16x16x32_bf16 v[76:79], v[208:211], v[172:175], v[76:79]
	v_mfma_f32_16x16x32_bf16 v[80:83], v[200:203], v[180:183], v[80:83]
	v_mfma_f32_16x16x32_bf16 v[84:87], v[208:211], v[180:183], v[84:87]
	s_setprio 0
	s_barrier
	ds_read_b128 v[152:155], v186 offset:49168
	ds_read_b128 v[156:159], v187 offset:49168
	ds_read_b128 v[160:163], v186 offset:51216
	ds_read_b128 v[164:167], v187 offset:51216
	ds_read_b128 v[168:171], v186 offset:53264
	ds_read_b128 v[172:175], v187 offset:53264
	ds_read_b128 v[176:179], v186 offset:55312
	ds_read_b128 v[180:183], v187 offset:55312
	s_barrier
	s_waitcnt lgkmcnt(0)
	s_setprio 1
	v_mfma_f32_16x16x32_bf16 v[88:91], v[0:3], v[152:155], v[88:91]
	v_mfma_f32_16x16x32_bf16 v[92:95], v[8:11], v[152:155], v[92:95]
	v_mfma_f32_16x16x32_bf16 v[96:99], v[0:3], v[160:163], v[96:99]
	v_mfma_f32_16x16x32_bf16 v[100:103], v[8:11], v[160:163], v[100:103]
	v_mfma_f32_16x16x32_bf16 v[104:107], v[0:3], v[168:171], v[104:107]
	v_mfma_f32_16x16x32_bf16 v[108:111], v[8:11], v[168:171], v[108:111]
	v_mfma_f32_16x16x32_bf16 v[112:115], v[0:3], v[176:179], v[112:115]
	v_mfma_f32_16x16x32_bf16 v[116:119], v[8:11], v[176:179], v[116:119]
	v_mfma_f32_16x16x32_bf16 v[88:91], v[4:7], v[156:159], v[88:91]
	v_mfma_f32_16x16x32_bf16 v[92:95], v[12:15], v[156:159], v[92:95]
	v_mfma_f32_16x16x32_bf16 v[96:99], v[4:7], v[164:167], v[96:99]
	v_mfma_f32_16x16x32_bf16 v[100:103], v[12:15], v[164:167], v[100:103]
	v_mfma_f32_16x16x32_bf16 v[104:107], v[4:7], v[172:175], v[104:107]
	v_mfma_f32_16x16x32_bf16 v[108:111], v[12:15], v[172:175], v[108:111]
	v_mfma_f32_16x16x32_bf16 v[112:115], v[4:7], v[180:183], v[112:115]
	v_mfma_f32_16x16x32_bf16 v[116:119], v[12:15], v[180:183], v[116:119]
	s_setprio 0
	s_setprio 1
	v_mfma_f32_16x16x32_bf16 v[120:123], v[196:199], v[152:155], v[120:123]
	v_mfma_f32_16x16x32_bf16 v[124:127], v[204:207], v[152:155], v[124:127]
	v_mfma_f32_16x16x32_bf16 v[128:131], v[196:199], v[160:163], v[128:131]
	v_mfma_f32_16x16x32_bf16 v[132:135], v[204:207], v[160:163], v[132:135]
	v_mfma_f32_16x16x32_bf16 v[136:139], v[196:199], v[168:171], v[136:139]
	v_mfma_f32_16x16x32_bf16 v[140:143], v[204:207], v[168:171], v[140:143]
	v_mfma_f32_16x16x32_bf16 v[144:147], v[196:199], v[176:179], v[144:147]
	v_mfma_f32_16x16x32_bf16 v[148:151], v[204:207], v[176:179], v[148:151]
	v_mfma_f32_16x16x32_bf16 v[120:123], v[200:203], v[156:159], v[120:123]
	v_mfma_f32_16x16x32_bf16 v[124:127], v[208:211], v[156:159], v[124:127]
	v_mfma_f32_16x16x32_bf16 v[128:131], v[200:203], v[164:167], v[128:131]
	v_mfma_f32_16x16x32_bf16 v[132:135], v[208:211], v[164:167], v[132:135]
	v_mfma_f32_16x16x32_bf16 v[136:139], v[200:203], v[172:175], v[136:139]
	v_mfma_f32_16x16x32_bf16 v[140:143], v[208:211], v[172:175], v[140:143]
	v_mfma_f32_16x16x32_bf16 v[144:147], v[200:203], v[180:183], v[144:147]
	v_mfma_f32_16x16x32_bf16 v[148:151], v[208:211], v[180:183], v[148:151]
	s_setprio 0
	s_barrier
	s_cmp_lg_u32 s33, 0
	s_cbranch_scc1 .Lgyd_epi
	s_barrier
; DI unsigned pk2(float lo, float hi) { const f32x2 v = {lo, hi}; return __builtin_bit_cast(unsigned, __builtin_convertvector(v, bf2_t)); }
;     bf16_t* Y = (bf16_t*)(p.ws + B_Y);
;     float* YS = (float*)(p.ws + B_YS);
;     const int lane = tid & 63, wave = __builtin_amdgcn_readfirstlane(tid >> 6), wm = wave >> 1, wn = wave & 1, r = lane & 15, q = lane >> 4;
; #pragma unroll
;     for (int mi = 0; mi < 4; ++mi) {
;         const int row = m0 + wm * 64 + mi * 16 + r;
; #pragma unroll
;         for (int ni = 0; ni < 4; ++ni) {
;             const int col = n0 + wn * 64 + ni * 16 + q * 4;
;             if (MODE == 0) {
;                 u32x2 w; w.x = pk2(acc[mi][ni][0], acc[mi][ni][1]); w.y = pk2(acc[mi][ni][2], acc[mi][ni][3]);
;                 *(u32x2*)(Y + (size_t)row * DM + col) = w;
.Lgyd_epi:
	s_cmp_eq_u32 s55, 0
	s_cbranch_scc0 .Lgyd_epi_unit
	s_lshl_b32 s1, s57, 19
	s_lshl_b32 s62, s58, 9
	s_add_u32 s1, s1, s62
	s_add_u32 s1, s1, 0xac20000
	s_add_u32 s2, s88, s1
	s_addc_u32 s3, s89, 0
	s_nop 7
	s_nop 7
	v_cvt_pk_bf16_f32 v152, v24, v25
	v_cvt_pk_bf16_f32 v153, v26, v27
	global_store_dwordx2 v237, v[152:153], s[2:3] offset:0
	v_cvt_pk_bf16_f32 v154, v28, v29
	v_cvt_pk_bf16_f32 v155, v30, v31
	global_store_dwordx2 v237, v[154:155], s[2:3] offset:32
	v_cvt_pk_bf16_f32 v156, v56, v57
	v_cvt_pk_bf16_f32 v157, v58, v59
	global_store_dwordx2 v237, v[156:157], s[2:3] offset:256
	v_cvt_pk_bf16_f32 v158, v60, v61
	v_cvt_pk_bf16_f32 v159, v62, v63
	global_store_dwordx2 v237, v[158:159], s[2:3] offset:288
	s_add_u32 s2, s2, 0x8000
	s_addc_u32 s3, s3, 0
	v_cvt_pk_bf16_f32 v160, v32, v33
	v_cvt_pk_bf16_f32 v161, v34, v35
	global_store_dwordx2 v237, v[160:161], s[2:3] offset:0
	v_cvt_pk_bf16_f32 v162, v36, v37
	v_cvt_pk_bf16_f32 v163, v38, v39
	global_store_dwordx2 v237, v[162:163], s[2:3] offset:32
	v_cvt_pk_bf16_f32 v164, v64, v65
	v_cvt_pk_bf16_f32 v165, v66, v67
	global_store_dwordx2 v237, v[164:165], s[2:3] offset:256
	v_cvt_pk_bf16_f32 v166, v68, v69
	v_cvt_pk_bf16_f32 v167, v70, v71
	global_store_dwordx2 v237, v[166:167], s[2:3] offset:288
	s_add_u32 s2, s2, 0x8000
	s_addc_u32 s3, s3, 0
	v_cvt_pk_bf16_f32 v152, v40, v41
	v_cvt_pk_bf16_f32 v153, v42, v43
	global_store_dwordx2 v237, v[152:153], s[2:3] offset:0
	v_cvt_pk_bf16_f32 v154, v44, v45
	v_cvt_pk_bf16_f32 v155, v46, v47
	global_store_dwordx2 v237, v[154:155], s[2:3] offset:32
	v_cvt_pk_bf16_f32 v156, v72, v73
	v_cvt_pk_bf16_f32 v157, v74, v75
	global_store_dwordx2 v237, v[156:157], s[2:3] offset:256
	v_cvt_pk_bf16_f32 v158, v76, v77
	v_cvt_pk_bf16_f32 v159, v78, v79
	global_store_dwordx2 v237, v[158:159], s[2:3] offset:288
	s_add_u32 s2, s2, 0x8000
	s_addc_u32 s3, s3, 0
	v_cvt_pk_bf16_f32 v160, v48, v49
	v_cvt_pk_bf16_f32 v161, v50, v51
	global_store_dwordx2 v237, v[160:161], s[2:3] offset:0
	v_cvt_pk_bf16_f32 v162, v52, v53
	v_cvt_pk_bf16_f32 v163, v54, v55
	global_store_dwordx2 v237, v[162:163], s[2:3] offset:32
	v_cvt_pk_bf16_f32 v164, v80, v81
	v_cvt_pk_bf16_f32 v165, v82, v83
	global_store_dwordx2 v237, v[164:165], s[2:3] offset:256
	v_cvt_pk_bf16_f32 v166, v84, v85
	v_cvt_pk_bf16_f32 v167, v86, v87
	global_store_dwordx2 v237, v[166:167], s[2:3] offset:288
	s_add_u32 s2, s2, 0x28000
	s_addc_u32 s3, s3, 0
	v_cvt_pk_bf16_f32 v152, v88, v89
	v_cvt_pk_bf16_f32 v153, v90, v91
	global_store_dwordx2 v237, v[152:153], s[2:3] offset:0
	v_cvt_pk_bf16_f32 v154, v92, v93
	v_cvt_pk_bf16_f32 v155, v94, v95
	global_store_dwordx2 v237, v[154:155], s[2:3] offset:32
	v_cvt_pk_bf16_f32 v156, v120, v121
	v_cvt_pk_bf16_f32 v157, v122, v123
	global_store_dwordx2 v237, v[156:157], s[2:3] offset:256
	v_cvt_pk_bf16_f32 v158, v124, v125
	v_cvt_pk_bf16_f32 v159, v126, v127
	global_store_dwordx2 v237, v[158:159], s[2:3] offset:288
	s_add_u32 s2, s2, 0x8000
	s_addc_u32 s3, s3, 0
	v_cvt_pk_bf16_f32 v160, v96, v97
	v_cvt_pk_bf16_f32 v161, v98, v99
	global_store_dwordx2 v237, v[160:161], s[2:3] offset:0
	v_cvt_pk_bf16_f32 v162, v100, v101
	v_cvt_pk_bf16_f32 v163, v102, v103
	global_store_dwordx2 v237, v[162:163], s[2:3] offset:32
	v_cvt_pk_bf16_f32 v164, v128, v129
	v_cvt_pk_bf16_f32 v165, v130, v131
	global_store_dwordx2 v237, v[164:165], s[2:3] offset:256
	v_cvt_pk_bf16_f32 v166, v132, v133
	v_cvt_pk_bf16_f32 v167, v134, v135
	global_store_dwordx2 v237, v[166:167], s[2:3] offset:288
	s_add_u32 s2, s2, 0x8000
	s_addc_u32 s3, s3, 0
	v_cvt_pk_bf16_f32 v152, v104, v105
	v_cvt_pk_bf16_f32 v153, v106, v107
	global_store_dwordx2 v237, v[152:153], s[2:3] offset:0
	v_cvt_pk_bf16_f32 v154, v108, v109
	v_cvt_pk_bf16_f32 v155, v110, v111
	global_store_dwordx2 v237, v[154:155], s[2:3] offset:32
	v_cvt_pk_bf16_f32 v156, v136, v137
	v_cvt_pk_bf16_f32 v157, v138, v139
	global_store_dwordx2 v237, v[156:157], s[2:3] offset:256
	v_cvt_pk_bf16_f32 v158, v140, v141
	v_cvt_pk_bf16_f32 v159, v142, v143
	global_store_dwordx2 v237, v[158:159], s[2:3] offset:288
	s_add_u32 s2, s2, 0x8000
	s_addc_u32 s3, s3, 0
	v_cvt_pk_bf16_f32 v160, v112, v113
	v_cvt_pk_bf16_f32 v161, v114, v115
	global_store_dwordx2 v237, v[160:161], s[2:3] offset:0
	v_cvt_pk_bf16_f32 v162, v116, v117
	v_cvt_pk_bf16_f32 v163, v118, v119
	global_store_dwordx2 v237, v[162:163], s[2:3] offset:32
	v_cvt_pk_bf16_f32 v164, v144, v145
	v_cvt_pk_bf16_f32 v165, v146, v147
	global_store_dwordx2 v237, v[164:165], s[2:3] offset:256
	v_cvt_pk_bf16_f32 v166, v148, v149
	v_cvt_pk_bf16_f32 v167, v150, v151
	global_store_dwordx2 v237, v[166:167], s[2:3] offset:288
	s_branch .Lgyd_epi_done
;     ...
;             } else if (MODE == 1) {
;                 *(f32x4*)(YS + (size_t)(row - NP) * DM + col) = acc[mi][ni];
;             } else {
;                 *(f32x4*)(YS + (size_t)part * NS * DM + (size_t)(row - NP) * DM + col) = acc[mi][ni];
;             }
;         }
;     }
; }
; DI void gemm_y(const Params& p, const bf16_t* A, int lda, size_t woff, int K, int kper, int bid, int nb, char* smem, const int tid) {
;     const bf16_t* Bt = (const bf16_t*)(p.ws + woff);
;     TileIter ti; ti.init(64, 8, bid, nb);
;     int tm, tn, tm2 = 0, tn2 = 0;
;     bool have = ti.next(tm, tn);
;     Ring rg; rg.st = 0; rg.primed = 0;
;     for (; have; tm = tm2, tn = tn2) {
;         have = ti.next(tm2, tn2);
;         const int m0 = tm * 256, n0 = tn * 128;
;         f32x4 acc[4][4]; zero_acc(acc);
;         gemm_stream(A, lda, Bt, K, K, m0, n0, have, tm2 * 256, tn2 * 128, smem, acc, tid, rg);
;         epi_y<0>(p, acc, m0, n0, tid);
;     }
;     const int S = (K / 64) / kper;
;     for (int u = bid; u < 8 * S; u += nb) {
;         const int tile = u / S, part = u - tile * S, m0 = NP, n0 = tile * 128;
;         f32x4 acc[4][4]; zero_acc(acc);
;         gemm_mainloop(A + part * kper * 64, lda, Bt + part * kper * 64, K, kper * 64, m0, n0, smem, acc, tid);
;         epi_y<2>(p, acc, m0, n0, tid, part);
;     }
.Lgyd_epi_unit:
	s_lshl_b32 s1, s57, 20
	s_lshl_b32 s62, s58, 10
	s_add_u32 s1, s1, s62
	s_add_u32 s1, s1, 0x12595000
	s_add_u32 s2, s88, s1
	s_addc_u32 s3, s89, 0
	v_lshlrev_b32_e32 v152, 1, v237
	s_nop 7
	s_nop 7
	global_store_dwordx4 v152, v[24:27], s[2:3] offset:0
	global_store_dwordx4 v152, v[28:31], s[2:3] offset:64
	global_store_dwordx4 v152, v[56:59], s[2:3] offset:512
	global_store_dwordx4 v152, v[60:63], s[2:3] offset:576
	s_add_u32 s2, s2, 0x10000
	s_addc_u32 s3, s3, 0
	global_store_dwordx4 v152, v[32:35], s[2:3] offset:0
	global_store_dwordx4 v152, v[36:39], s[2:3] offset:64
	global_store_dwordx4 v152, v[64:67], s[2:3] offset:512
	global_store_dwordx4 v152, v[68:71], s[2:3] offset:576
	s_add_u32 s2, s2, 0x10000
	s_addc_u32 s3, s3, 0
	global_store_dwordx4 v152, v[40:43], s[2:3] offset:0
	global_store_dwordx4 v152, v[44:47], s[2:3] offset:64
	global_store_dwordx4 v152, v[72:75], s[2:3] offset:512
	global_store_dwordx4 v152, v[76:79], s[2:3] offset:576
	s_add_u32 s2, s2, 0x10000
	s_addc_u32 s3, s3, 0
	global_store_dwordx4 v152, v[48:51], s[2:3] offset:0
	global_store_dwordx4 v152, v[52:55], s[2:3] offset:64
	global_store_dwordx4 v152, v[80:83], s[2:3] offset:512
	global_store_dwordx4 v152, v[84:87], s[2:3] offset:576
	s_add_u32 s2, s2, 0x50000
	s_addc_u32 s3, s3, 0
	global_store_dwordx4 v152, v[88:91], s[2:3] offset:0
	global_store_dwordx4 v152, v[92:95], s[2:3] offset:64
	global_store_dwordx4 v152, v[120:123], s[2:3] offset:512
	global_store_dwordx4 v152, v[124:127], s[2:3] offset:576
	s_add_u32 s2, s2, 0x10000
	s_addc_u32 s3, s3, 0
	global_store_dwordx4 v152, v[96:99], s[2:3] offset:0
	global_store_dwordx4 v152, v[100:103], s[2:3] offset:64
	global_store_dwordx4 v152, v[128:131], s[2:3] offset:512
	global_store_dwordx4 v152, v[132:135], s[2:3] offset:576
	s_add_u32 s2, s2, 0x10000
	s_addc_u32 s3, s3, 0
	global_store_dwordx4 v152, v[104:107], s[2:3] offset:0
	global_store_dwordx4 v152, v[108:111], s[2:3] offset:64
	global_store_dwordx4 v152, v[136:139], s[2:3] offset:512
	global_store_dwordx4 v152, v[140:143], s[2:3] offset:576
	s_add_u32 s2, s2, 0x10000
	s_addc_u32 s3, s3, 0
	global_store_dwordx4 v152, v[112:115], s[2:3] offset:0
	global_store_dwordx4 v152, v[116:119], s[2:3] offset:64
	global_store_dwordx4 v152, v[144:147], s[2:3] offset:512
	global_store_dwordx4 v152, v[148:151], s[2:3] offset:576
	s_nop 1
.Lgyd_epi_done:
	s_cmp_eq_u32 s54, 0
	s_cbranch_scc1 .LBB0_860
	s_mov_b32 s51, s76
	s_mov_b32 s57, s59
	s_mov_b32 s58, s60
	s_mov_b32 s55, s93
	s_branch .Lgyd_item

; DI void gemm_stream2(const bf16_t* __restrict__ A, int lda, const bf16_t* __restrict__ Bt, int ldb, int K, int m0, int n0, ...
;     ...
;     const bf16_t* ga = A + (size_t)(m0 + wave * 32 + (lane >> 3)) * lda;
;     const bf16_t* gb = Bt + (size_t)(n0 + wave * 16 + (lane >> 3)) * ldb;
;     const bf16_t* gan = An + (size_t)(m0n + wave * 32 + (lane >> 3)) * ldan;
;     const bf16_t* gbn = Btn + (size_t)(n0n + wave * 16 + (lane >> 3)) * ldbn;
;     const unsigned wa = (unsigned)wave * 4096u, wbb = 32768u + (unsigned)wave * 2048u;
; DI void gemm_y(const Params& p, const bf16_t* A, int lda, size_t woff, int K, int kper, int bid, int nb, char* smem, const int tid) {
;     const bf16_t* Bt = (const bf16_t*)(p.ws + woff);
;     TileIter ti; ti.init(64, 8, bid, nb);
;     int tm, tn, tm2 = 0, tn2 = 0;
;     bool have = ti.next(tm, tn);
;     Ring rg; rg.st = 0; rg.primed = 0;
;     for (; have; tm = tm2, tn = tn2) {
;         have = ti.next(tm2, tn2);
;         const int m0 = tm * 256, n0 = tn * 128;
;         f32x4 acc[4][4]; zero_acc(acc);
;         gemm_stream(A, lda, Bt, K, K, m0, n0, have, tm2 * 256, tn2 * 128, smem, acc, tid, rg);
;         epi_y<0>(p, acc, m0, n0, tid);
;     }
;     const int S = (K / 64) / kper;
;     for (int u = bid; u < 8 * S; u += nb) {
;         const int tile = u / S, part = u - tile * S, m0 = NP, n0 = tile * 128;
;         f32x4 acc[4][4]; zero_acc(acc);
;         gemm_mainloop(A + part * kper * 64, lda, Bt + part * kper * 64, K, kper * 64, m0, n0, smem, acc, tid);
;         epi_y<2>(p, acc, m0, n0, tid, part);
;     }
.Lgyo_ranged:
	s_cmp_lt_u32 s51, s52
	s_cbranch_scc1 .Lgyo_first_main
	s_cmp_lt_u32 s96, 32
	s_cbranch_scc0 .LBB0_860
	s_mov_b32 s55, 1
	s_mov_b32 s51, s96
	s_lshr_b32 s58, s51, 3
	s_and_b32 s57, s51, 7
	s_mul_i32 s2, s10, 0x8000
	s_lshl_b32 s3, s57, 8
	s_add_u32 s1, s2, 0x2000000
	s_add_u32 s1, s1, s3
	s_add_u32 s66, s88, s1
	s_addc_u32 s67, s89, 0
	s_add_u32 s66, s66, 0x3240000
	s_addc_u32 s67, s67, 0
	s_add_u32 s68, s66, 0x40000
	s_addc_u32 s69, s67, 0
	s_mul_i32 s1, s58, 0x80000
	s_add_u32 s1, s1, s2
	s_add_u32 s1, s1, s3
	s_add_u32 s1, s1, s61
	s_add_u32 s70, s88, s1
	s_addc_u32 s71, s89, 0
	s_add_u32 s72, s70, 0x40000
	s_addc_u32 s73, s71, 0
	s_branch .Lgyo_lanes
.Lgyo_first_main:
	s_mov_b32 s55, 0
	s_lshr_b32 s1, s51, 5
	s_and_b32 s2, s51, 31
	s_lshr_b32 s58, s2, 3
	s_and_b32 s2, s2, 7
	s_lshl_b32 s1, s1, 3
	s_add_i32 s57, s1, s2
	s_mul_i32 s2, s10, 0x8000
	s_mul_i32 s1, s57, 0x80000
	s_add_u32 s1, s1, s2
	s_add_u32 s66, s88, s1
	s_addc_u32 s67, s89, 0
	s_add_u32 s66, s66, 0x3240000
	s_addc_u32 s67, s67, 0
	s_add_u32 s68, s66, 0x40000
	s_addc_u32 s69, s67, 0
	s_mul_i32 s1, s58, 0x80000
	s_add_u32 s1, s1, s2
	s_add_u32 s1, s1, s61
	s_add_u32 s70, s88, s1
	s_addc_u32 s71, s89, 0
	s_add_u32 s72, s70, 0x40000
	s_addc_u32 s73, s71, 0
.Lgyo_lanes:
	v_and_b32_e32 v190, 63, v193
	v_and_b32_e32 v191, 15, v190
	v_lshrrev_b32_e32 v17, 4, v190
	v_lshrrev_b32_e32 v18, 3, v190
	v_and_b32_e32 v19, 7, v190
	v_xor_b32_e32 v195, v19, v17
	v_lshlrev_b32_e32 v195, 4, v195
	s_mov_b32 s1, 0x800
	v_mad_u32_u24 v184, v18, s1, v195
	v_or_b32_e32 v195, 4, v17
	v_xor_b32_e32 v195, v19, v195
	v_lshlrev_b32_e32 v195, 4, v195
	v_add_u32_e32 v227, 8, v18
	v_mad_u32_u24 v185, v227, s1, v195
	v_lshrrev_b32_e32 v195, 1, v191
	v_xor_b32_e32 v195, v17, v195
	v_lshlrev_b32_e32 v195, 4, v195
	s_lshl_b32 s1, s33, 6
	v_add_u32_e32 v227, s1, v191
	v_lshl_add_u32 v186, v227, 7, v195
	v_xor_b32_e32 v187, 64, v186
	v_lshlrev_b32_e32 v228, 11, v227
	s_lshl_b32 s1, s36, 5
	v_add_u32_e32 v227, s1, v191
	v_lshl_add_u32 v188, v227, 7, v195
	v_add_u32_e32 v188, 0x10000, v188
	v_xor_b32_e32 v189, 64, v188
	s_lshl_b32 s1, s36, 6
	v_lshl_add_u32 v229, v17, 3, s1
	v_add_u32_e32 v237, v228, v229
	s_add_i32 m0, s39, 0x10000
	s_nop 0
	global_load_lds_dwordx4 v184, s[70:71]
	s_add_i32 m0, s39, 0x10400
	s_nop 0
	global_load_lds_dwordx4 v185, s[70:71]
	s_add_u32 s70, s70, 0x80
	s_addc_u32 s71, s71, 0
	s_add_i32 m0, s39, 0x0
	s_nop 0
	global_load_lds_dwordx4 v184, s[66:67]
	s_add_i32 m0, s39, 0x400
	s_nop 0
	global_load_lds_dwordx4 v185, s[66:67]
	s_add_u32 s66, s66, 0x80
	s_addc_u32 s67, s67, 0
	s_add_i32 m0, s39, 0x14000
	s_nop 0
	global_load_lds_dwordx4 v184, s[72:73]
	s_add_i32 m0, s39, 0x14400
	s_nop 0
	global_load_lds_dwordx4 v185, s[72:73]
	s_add_u32 s72, s72, 0x80
	s_addc_u32 s73, s73, 0
	s_add_i32 m0, s39, 0x4000
	s_nop 0
	global_load_lds_dwordx4 v184, s[68:69]
	s_add_i32 m0, s39, 0x4400
	s_nop 0
	global_load_lds_dwordx4 v185, s[68:69]
	s_add_u32 s68, s68, 0x80
	s_addc_u32 s69, s69, 0
	s_cmp_eq_u32 s33, 0
	s_cbranch_scc1 .Lgyo_lead
	s_barrier

;     DI bool next(int& tm, int& tn) {
;         if (L >= end) return false;
;         const int gsz = 8 * ntn, grp = L / gsz, rem = L - grp * gsz, rows = min(8, ntm - grp * 8);
;         tn = rem / rows; tm = grp * 8 + (rem - tn * rows);
;         L += step; return true;
;     }
; DI void gemm_y(const Params& p, const bf16_t* A, int lda, size_t woff, int K, int kper, int bid, int nb, char* smem, const int tid) {
;     ...
;     for (; have; tm = tm2, tn = tn2) {
;         have = ti.next(tm2, tn2);
;         const int m0 = tm * 256, n0 = tn * 128;
;         f32x4 acc[4][4]; zero_acc(acc);
;         gemm_stream(A, lda, Bt, K, K, m0, n0, have, tm2 * 256, tn2 * 128, smem, acc, tid, rg);
.Lgyo_item:
	s_cmp_eq_u32 s55, 0
	s_cbranch_scc0 .Lgyo_nx_unit
	s_add_u32 s76, s51, s53
	s_cmp_lt_u32 s76, s52
	s_cbranch_scc0 .Lgyo_nx_first_unit
	s_mov_b32 s54, 1
	s_mov_b32 s93, 0
	s_lshr_b32 s1, s76, 5
	s_and_b32 s2, s76, 31
	s_lshr_b32 s60, s2, 3
	s_and_b32 s2, s2, 7
	s_lshl_b32 s1, s1, 3
	s_add_i32 s59, s1, s2
	s_mul_i32 s2, s10, 0x8000
	s_mul_i32 s1, s59, 0x80000
	s_add_u32 s1, s1, s2
	s_add_u32 s74, s88, s1
	s_addc_u32 s75, s89, 0
	s_add_u32 s74, s74, 0x3240000
	s_addc_u32 s75, s75, 0
	s_add_u32 s78, s74, 0x40000
	s_addc_u32 s79, s75, 0
	s_mul_i32 s1, s60, 0x80000
	s_add_u32 s1, s1, s2
	s_add_u32 s1, s1, s61
	s_add_u32 s80, s88, s1
	s_addc_u32 s81, s89, 0
	s_add_u32 s82, s80, 0x40000
	s_addc_u32 s83, s81, 0
	s_branch .Lgyo_nx_done

; DI void zero_acc(f32x4 (&acc)[4][4]) {
; #pragma unroll
;     for (int i = 0; i < 4; ++i)
; #pragma unroll
;         for (int j = 0; j < 4; ++j) acc[i][j] = (f32x4){0.f, 0.f, 0.f, 0.f};
; }
; DI void gemm_y(const Params& p, const bf16_t* A, int lda, size_t woff, int K, int kper, int bid, int nb, char* smem, const int tid) {
;     ...
;     const int S = (K / 64) / kper;
;     for (int u = bid; u < 8 * S; u += nb) {
;         const int tile = u / S, part = u - tile * S, m0 = NP, n0 = tile * 128;
;         f32x4 acc[4][4]; zero_acc(acc);
;         gemm_mainloop(A + part * kper * 64, lda, Bt + part * kper * 64, K, kper * 64, m0, n0, smem, acc, tid);
;         epi_y<2>(p, acc, m0, n0, tid, part);
;     }
.Lgyo_nx_unit_chk:
	s_mov_b32 s54, 0
	s_cmp_lt_u32 s76, 32
	s_cbranch_scc0 .Lgyo_nx_done
	s_mov_b32 s54, 1
	s_mov_b32 s93, 1
	s_lshr_b32 s60, s76, 3
	s_and_b32 s59, s76, 7
	s_mul_i32 s2, s10, 0x8000
	s_lshl_b32 s3, s59, 8
	s_add_u32 s1, s2, 0x2000000
	s_add_u32 s1, s1, s3
	s_add_u32 s74, s88, s1
	s_addc_u32 s75, s89, 0
	s_add_u32 s74, s74, 0x3240000
	s_addc_u32 s75, s75, 0
	s_add_u32 s78, s74, 0x40000
	s_addc_u32 s79, s75, 0
	s_mul_i32 s1, s60, 0x80000
	s_add_u32 s1, s1, s2
	s_add_u32 s1, s1, s3
	s_add_u32 s1, s1, s61
	s_add_u32 s80, s88, s1
	s_addc_u32 s81, s89, 0
	s_add_u32 s82, s80, 0x40000
	s_addc_u32 s83, s81, 0
.Lgyo_nx_done:
	v_mov_b64_e32 v[24:25], 0
	v_mov_b64_e32 v[26:27], 0
	v_mov_b64_e32 v[28:29], 0
	v_mov_b64_e32 v[30:31], 0
	v_mov_b64_e32 v[32:33], 0
	v_mov_b64_e32 v[34:35], 0
	v_mov_b64_e32 v[36:37], 0
	v_mov_b64_e32 v[38:39], 0
	v_mov_b64_e32 v[40:41], 0
	v_mov_b64_e32 v[42:43], 0
	v_mov_b64_e32 v[44:45], 0
	v_mov_b64_e32 v[46:47], 0
	v_mov_b64_e32 v[48:49], 0
	v_mov_b64_e32 v[50:51], 0
	v_mov_b64_e32 v[52:53], 0
	v_mov_b64_e32 v[54:55], 0
	v_mov_b64_e32 v[56:57], 0
	v_mov_b64_e32 v[58:59], 0
	v_mov_b64_e32 v[60:61], 0
	v_mov_b64_e32 v[62:63], 0
	v_mov_b64_e32 v[64:65], 0
	v_mov_b64_e32 v[66:67], 0
	v_mov_b64_e32 v[68:69], 0
	v_mov_b64_e32 v[70:71], 0
	v_mov_b64_e32 v[72:73], 0
	v_mov_b64_e32 v[74:75], 0
	v_mov_b64_e32 v[76:77], 0
	v_mov_b64_e32 v[78:79], 0
	v_mov_b64_e32 v[80:81], 0
	v_mov_b64_e32 v[82:83], 0
	v_mov_b64_e32 v[84:85], 0
	v_mov_b64_e32 v[86:87], 0
	v_mov_b64_e32 v[88:89], 0
	v_mov_b64_e32 v[90:91], 0
	v_mov_b64_e32 v[92:93], 0
	v_mov_b64_e32 v[94:95], 0
	v_mov_b64_e32 v[96:97], 0
	v_mov_b64_e32 v[98:99], 0
	v_mov_b64_e32 v[100:101], 0
	v_mov_b64_e32 v[102:103], 0
	v_mov_b64_e32 v[104:105], 0
	v_mov_b64_e32 v[106:107], 0
	v_mov_b64_e32 v[108:109], 0
	v_mov_b64_e32 v[110:111], 0
	v_mov_b64_e32 v[112:113], 0
	v_mov_b64_e32 v[114:115], 0
	v_mov_b64_e32 v[116:117], 0
	v_mov_b64_e32 v[118:119], 0
	v_mov_b64_e32 v[120:121], 0
	v_mov_b64_e32 v[122:123], 0
	v_mov_b64_e32 v[124:125], 0
	v_mov_b64_e32 v[126:127], 0
	v_mov_b64_e32 v[128:129], 0
	v_mov_b64_e32 v[130:131], 0
	v_mov_b64_e32 v[132:133], 0
	v_mov_b64_e32 v[134:135], 0
	v_mov_b64_e32 v[136:137], 0
	v_mov_b64_e32 v[138:139], 0
	v_mov_b64_e32 v[140:141], 0
	v_mov_b64_e32 v[142:143], 0
	v_mov_b64_e32 v[144:145], 0
	v_mov_b64_e32 v[146:147], 0
	v_mov_b64_e32 v[148:149], 0
	v_mov_b64_e32 v[150:151], 0
	s_cmp_eq_u32 s55, 0
	s_cselect_b32 s0, 7, 0
	s_add_u32 s0, s0, s54
	s_cmp_eq_u32 s0, 0
	s_cbranch_scc1 .Lgyo_kdone
